# mlstm_out: the 64 gate values (tanh/log1p/exp) computed by the 64 lanes of wave 0 instead of every 4th lane of all four waves
# speedup vs baseline: 1.0010x; 1.0010x over previous
; __device__ __forceinline__ float bf2f(bf16_t h) { return __uint_as_float(((unsigned)h) << 16); }
; __device__ __forceinline__ void mlstm_out_unit(const Params& p, int layer, int uci, char* smem) {
;     ...
;         const int s = tid >> 2, part = tid & 3;
;         const int t = step_tok(ci * 64 + s, d);
;         const int lo = t < CTX ? 0 : CTX, hi = t < CTX ? CTX : TT;
;         const bool hp = t > lo, hn = t + 1 < hi;
;         const bf16_t* zr = zm + ((size_t)b * TT + t) * 784;
;         if (part < 2) { const int kc = part * 16;
;             *(uint4*)(smem + MO_Q + s * 80 + kc * 2) = conv8_bf(zr, h * 32 + kc, hp, hn, cw, cb, 0.17677669529663687f);
;             *(uint4*)(smem + MO_Q + s * 80 + kc * 2 + 16) = conv8_bf(zr, h * 32 + kc + 8, hp, hn, cw, cb, 0.17677669529663687f); }
;         else { const int kc = (part - 2) * 16;
;             *(uint4*)(smem + MO_K + s * 80 + kc * 2) = conv8_bf(zr, 128 + h * 32 + kc, hp, hn, cw, cb, 1.f);
;             *(uint4*)(smem + MO_K + s * 80 + kc * 2 + 16) = conv8_bf(zr, 128 + h * 32 + kc + 8, hp, hn, cw, cb, 1.f); }
;         {
;             const bf16x8 v0 = *(const bf16x8*)(zr + 256 + h * 64 + part * 16), v1 = *(const bf16x8*)(zr + 256 + h * 64 + part * 16 + 8);
; #pragma unroll
;             for (int j = 0; j < 8; ++j) { *(bf16_t*)(smem + MO_V + (part * 16 + j) * 144 + s * 2) = (bf16_t)v0[j]; *(bf16_t*)(smem + MO_V + (part * 16 + 8 + j) * 144 + s * 2) = (bf16_t)v1[j]; }
;         }
;         if (part == 0) {
;             const float ib = p.in[31][(size_t)layer * 8 + d * 4 + h], fb = p.in[32][(size_t)layer * 8 + d * 4 + h];
;             const float ig = bf2f(zr[768 + d * 8 + h]) + ib, fg = bf2f(zr[768 + d * 8 + 4 + h]) + fb;
;             F[64 + s] = 15.f * tanhf(ig * (1.f / 15.f));
;             const float fc = 15.f * tanhf(fg * (1.f / 15.f));
;             F[s] = fminf(fc, 0.f) - log1pf(expf(-fabsf(fc)));
;         }
.LBB0_504:
	s_or_b64 exec, exec, s[34:35]
	s_lshl_b32 s88, s50, 7
	s_waitcnt vmcnt(1)
	v_cvt_pk_bf16_f32 v7, v0, v1
	v_lshl_add_u64 v[0:1], v[32:33], 0, s[88:89]
	v_lshlrev_b32_e32 v104, 1, v30
	v_cvt_pk_bf16_f32 v6, v34, v35
	v_cvt_pk_bf16_f32 v8, v4, v5
	v_cvt_pk_bf16_f32 v9, v2, v3
	v_lshl_add_u64 v[4:5], v[0:1], 0, v[104:105]
	v_lshlrev_b32_e32 v0, 1, v31
	ds_write_b128 v41, v[6:9] offset:16
	v_mad_u32_u24 v8, v29, s33, v0
	global_load_dwordx4 v[0:3], v[4:5], off offset:512
	s_ashr_i32 s1, s0, 31
	global_load_dwordx4 v[4:7], v[4:5], off offset:528
	s_mul_hi_i32 s98, s0, 0x78787879
	s_lshr_b32 s99, s98, 31
	s_ashr_i32 s98, s98, 5
	s_add_i32 s98, s98, s99
	s_mul_i32 s99, s98, 0x44
	s_sub_i32 s99, s0, s99
	s_ashr_i32 s98, s98, 3
	v_readlane_b32 s100, v252, 2
	v_readlane_b32 s101, v252, 3
	v_lshl_add_u32 v244, s99, 6, v28
	v_cmp_lt_i32_e32 vcc, s2, v244
	s_cmp_eq_u32 s51, 0
	v_cndmask_b32_e32 v245, v196, v197, vcc
	v_sub_u32_e32 v245, v245, v244
	s_cselect_b64 vcc, -1, 0
	v_mov_b64_e32 v[246:247], s[100:101]
	v_cndmask_b32_e32 v244, v245, v244, vcc
	v_ashrrev_i32_e32 v245, 31, v244
	s_movk_i32 s99, 0x620
	v_mad_i64_i32 v[244:245], s[100:101], s98, v204, v[244:245]
	s_nop 1
	v_mad_u64_u32 v[246:247], s[100:101], v244, s99, v[246:247]
	v_mad_i32_i24 v247, v245, s99, v247
	v_cmp_gt_u32_e32 vcc, 64, v28
	s_waitcnt vmcnt(1)
	ds_write_b16 v8, v0 offset:10240
	s_waitcnt vmcnt(0)
	ds_write_b16 v8, v4 offset:11392
	ds_write_b16_d16_hi v8, v0 offset:10384
	ds_write_b16_d16_hi v8, v4 offset:11536
	ds_write_b16 v8, v1 offset:10528
	ds_write_b16 v8, v5 offset:11680
	ds_write_b16_d16_hi v8, v1 offset:10672
	ds_write_b16_d16_hi v8, v5 offset:11824
	ds_write_b16 v8, v2 offset:10816
	ds_write_b16 v8, v6 offset:11968
	ds_write_b16_d16_hi v8, v2 offset:10960
	ds_write_b16_d16_hi v8, v6 offset:12112
	ds_write_b16 v8, v3 offset:11104
	ds_write_b16 v8, v7 offset:12256
	ds_write_b16_d16_hi v8, v3 offset:11248
	ds_write_b16_d16_hi v8, v7 offset:12400
	s_and_saveexec_b64 s[34:35], vcc
	s_cbranch_execz .LBB0_514
	s_lshl_b32 s30, s51, 2
	v_readlane_b32 s4, v254, 42
	s_or_b32 s30, s30, s50
	v_readlane_b32 s5, v254, 43
	s_or_b32 s30, s4, s30
	s_mov_b32 s31, s5
	v_readlane_b32 s4, v250, 34
	s_lshl_b64 s[30:31], s[30:31], 2
	v_readlane_b32 s18, v250, 48
	v_readlane_b32 s5, v250, 35
	v_readlane_b32 s6, v250, 36
	v_readlane_b32 s7, v250, 37
	v_readlane_b32 s8, v250, 38
	v_readlane_b32 s9, v250, 39
	v_readlane_b32 s10, v250, 40
	v_readlane_b32 s11, v250, 41
	v_readlane_b32 s19, v250, 49
	s_add_u32 s44, s18, s30
	s_addc_u32 s45, s19, s31
	s_mov_b64 s[4:5], s[20:21]
	s_add_u32 s30, s4, s30
	s_addc_u32 s31, s5, s31
	global_load_dword v1, v105, s[44:45]
	global_load_dword v0, v105, s[30:31]
	s_lshl_b32 s30, s50, 1
	s_lshl_b32 s31, s51, 4
	s_or_b32 s88, s31, s30
	v_lshl_add_u64 v[2:3], v[246:247], 0, s[88:89]
	global_load_ushort v4, v[2:3], off offset:1536
	v_readlane_b32 s12, v250, 42
	v_readlane_b32 s13, v250, 43
	v_readlane_b32 s14, v250, 44
	v_readlane_b32 s15, v250, 45
	v_readlane_b32 s16, v250, 46
	v_readlane_b32 s17, v250, 47
	s_mov_b64 s[6:7], s[22:23]
	s_mov_b64 s[8:9], s[24:25]
	s_mov_b64 s[10:11], s[26:27]
	s_waitcnt vmcnt(0)
	v_lshlrev_b32_e32 v4, 16, v4
	v_add_f32_e32 v4, v1, v4
	global_load_ushort v1, v[2:3], off offset:1544
	v_mul_f32_e32 v2, 0x3d888889, v4
	v_cmp_nlt_f32_e64 s[30:31], |v2|, s3
	s_and_saveexec_b64 s[44:45], s[30:31]
	s_xor_b64 s[44:45], exec, s[44:45]
	s_cbranch_execz .LBB0_507
	v_add_f32_e64 v3, |v2|, |v2|
	v_mul_f32_e32 v4, 0x3fb8aa3b, v3
	v_rndne_f32_e32 v5, v4
	v_sub_f32_e32 v6, v4, v5
	v_fma_f32 v4, v3, s37, -v4
	v_fmac_f32_e32 v4, 0x32a5705f, v3
	v_add_f32_e32 v4, v6, v4
	v_cvt_i32_f32_e32 v5, v5
	v_exp_f32_e32 v4, v4
	v_cmp_ngt_f32_e32 vcc, s38, v3
	v_ldexp_f32 v4, v4, v5
	s_nop 0
	v_cndmask_b32_e32 v4, 0, v4, vcc
	v_cmp_nlt_f32_e32 vcc, s39, v3
	s_nop 1
	v_cndmask_b32_e32 v3, v202, v4, vcc
	v_add_f32_e32 v3, 1.0, v3
	v_rcp_f32_e32 v3, v3
	s_nop 0
	v_fma_f32 v3, v3, -2.0, 1.0
.LBB0_507:
	s_andn2_saveexec_b64 s[30:31], s[44:45]
	v_mul_f32_e32 v3, v2, v2
	v_fmamk_f32 v4, v3, 0xbbbac73d, v188
	v_fmaak_f32 v4, v3, v4, 0xbd5c1c4e
	v_fmaak_f32 v4, v3, v4, 0x3e088382
	v_fmaak_f32 v4, v3, v4, 0xbeaaaa99
	v_mul_f32_e64 v4, |v2|, v4
	v_fma_f32 v3, v3, v4, |v2|
	s_or_b64 exec, exec, s[30:31]
	s_waitcnt vmcnt(0)
	v_lshlrev_b32_e32 v1, 16, v1
	v_add_f32_e32 v1, v0, v1
	s_brev_b32 s4, -2
	v_bfi_b32 v0, s4, v3, v2
	v_mul_f32_e32 v1, 0x3d888889, v1
	v_mul_f32_e32 v2, 0x41700000, v0
	v_lshlrev_b32_e32 v0, 2, v28
	v_cmp_nlt_f32_e64 s[30:31], |v1|, s3
	ds_write_b32 v0, v2 offset:26112
	s_and_saveexec_b64 s[44:45], s[30:31]
	v_readlane_b32 s16, v255, 24
	v_readlane_b32 s18, v255, 26
	v_readlane_b32 s12, v254, 13
	s_xor_b64 s[44:45], exec, s[44:45]
	v_readlane_b32 s17, v255, 25
	v_readlane_b32 s19, v255, 27
	v_readlane_b32 s13, v254, 14
	s_mov_b32 s14, s82
	s_cbranch_execz .LBB0_511
	v_add_f32_e64 v2, |v1|, |v1|
	v_mul_f32_e32 v3, 0x3fb8aa3b, v2
	v_rndne_f32_e32 v4, v3
	v_sub_f32_e32 v5, v3, v4
	v_fma_f32 v3, v2, s37, -v3
	v_fmac_f32_e32 v3, 0x32a5705f, v2
	v_add_f32_e32 v3, v5, v3
	v_cvt_i32_f32_e32 v4, v4
	v_exp_f32_e32 v3, v3
	v_cmp_ngt_f32_e32 vcc, s38, v2
	v_ldexp_f32 v3, v3, v4
	s_nop 0
	v_cndmask_b32_e32 v3, 0, v3, vcc
	v_cmp_nlt_f32_e32 vcc, s39, v2
	s_nop 1
	v_cndmask_b32_e32 v2, v202, v3, vcc
	v_add_f32_e32 v2, 1.0, v2
	v_rcp_f32_e32 v2, v2
	s_nop 0
	v_fma_f32 v2, v2, -2.0, 1.0
